# gemm_in cq/ck/cv column tiles: own epilogue for both tiles with paired 16-byte bf16 stores (f32 state rows unchanged)
# speedup vs baseline: 1.0362x; 1.0067x over previous
.Lg2_c17:
	s_cmp_lt_u32 s37, 17
	s_cbranch_scc1 .Lg2_2p
	s_sub_i32 s3, s37, 17
	s_lshr_b32 s20, s3, 2
	s_and_b32 s3, s3, 3
	s_lshl_b32 s2, s20, 3
	s_add_u32 s92, s84, s2
	s_addc_u32 s93, s85, 0
	s_load_dwordx2 s[92:93], s[92:93], 0x180
	s_load_dwordx2 s[98:99], s[84:85], 0xd8
	v_lshrrev_b32_e32 v148, 7, v196
	v_and_b32_e32 v149, 15, v196
	v_lshl_or_b32 v148, v148, 6, v149
	v_bfe_u32 v149, v196, 6, 1
	v_bfe_u32 v150, v196, 4, 2
	v_lshlrev_b32_e32 v160, 11, v148
	v_lshl_add_u32 v160, v149, 8, v160
	v_lshl_add_u32 v160, v150, 4, v160
	v_add_u32_e32 v161, 0x8000, v160
	v_add_u32_e32 v162, 0x10000, v160
	v_add_u32_e32 v163, 0x18000, v160
	v_lshlrev_b32_e32 v148, 10, v148
	v_lshlrev_b32_e32 v149, 7, v149
	v_lshl_or_b32 v149, v150, 3, v149
	v_and_b32_e32 v150, 1, v150
	v_mul_u32_u24_e32 v150, 24, v150
	v_add3_u32 v156, v148, v149, v150
	v_add_u32_e32 v157, 0x4000, v156
	v_add_u32_e32 v158, 0x8000, v156
	v_add_u32_e32 v159, 0xc000, v156
	v_readlane_b32 s21, v249, 52
	s_waitcnt lgkmcnt(0)
	s_lshl_b32 s2, s0, 17
	s_lshl_b32 s38, s3, 8
	s_add_i32 s2, s2, s38
	s_add_u32 s96, s92, s2
	s_addc_u32 s97, s93, 0
	s_cmp_lt_u32 s0, 0x80
	s_cbranch_scc0 .Lg2_cs0
	s_lshl_b32 s2, s21, 25
	s_lshl_b32 s38, s0, 18
	s_add_i32 s2, s2, s38
	s_cmp_eq_u32 s20, 1
	s_mov_b32 s38, 0xa500000
	s_cmov_b32 s38, 0x6500000
	s_branch .Lg2_ct0
.Lg2_cs0:
	s_lshl_b32 s2, s21, 19
	s_sub_i32 s38, s0, 0x80
	s_lshl_b32 s38, s38, 18
	s_add_i32 s2, s2, s38
	s_cmp_eq_u32 s20, 1
	s_mov_b32 s38, 0xe690000
	s_cmov_b32 s38, 0xe590000
.Lg2_ct0:
	s_add_u32 s2, s2, s38
	s_lshl_b32 s38, s3, 9
	s_add_u32 s2, s2, s38
	s_add_u32 s88, s98, s2
	s_addc_u32 s89, s99, 0
	s_cmp_eq_u32 s20, 0
	s_cbranch_scc1 .Lg2_cb0
	global_store_dwordx4 v160, v[62:65], s[88:89] nt
	global_store_dwordx4 v160, v[58:61], s[88:89] offset:64 nt
	global_store_dwordx4 v160, v[54:57], s[88:89] offset:128 nt
	global_store_dwordx4 v160, v[50:53], s[88:89] offset:192 nt
	global_store_dwordx4 v161, v[46:49], s[88:89] nt
	global_store_dwordx4 v161, v[42:45], s[88:89] offset:64 nt
	global_store_dwordx4 v161, v[38:41], s[88:89] offset:128 nt
	global_store_dwordx4 v161, v[34:37], s[88:89] offset:192 nt
	global_store_dwordx4 v162, v[30:33], s[88:89] nt
	global_store_dwordx4 v162, v[26:29], s[88:89] offset:64 nt
	global_store_dwordx4 v162, v[22:25], s[88:89] offset:128 nt
	global_store_dwordx4 v162, v[18:21], s[88:89] offset:192 nt
	global_store_dwordx4 v163, v[14:17], s[88:89] nt
	global_store_dwordx4 v163, v[10:13], s[88:89] offset:64 nt
	global_store_dwordx4 v163, v[6:9], s[88:89] offset:128 nt
	global_store_dwordx4 v163, v[2:5], s[88:89] offset:192 nt
.Lg2_cb0:
	v_cvt_pk_bf16_f32 v164, v62, v63
	v_cvt_pk_bf16_f32 v165, v64, v65
	v_cvt_pk_bf16_f32 v166, v58, v59
	v_cvt_pk_bf16_f32 v167, v60, v61
	s_nop 1
	v_permlane16_swap_b32 v164, v166
	v_permlane16_swap_b32 v165, v167
	s_nop 1
	global_store_dwordx4 v156, v[164:167], s[96:97]
	v_cvt_pk_bf16_f32 v168, v54, v55
	v_cvt_pk_bf16_f32 v169, v56, v57
	v_cvt_pk_bf16_f32 v170, v50, v51
	v_cvt_pk_bf16_f32 v171, v52, v53
	s_nop 1
	v_permlane16_swap_b32 v168, v170
	v_permlane16_swap_b32 v169, v171
	s_nop 1
	global_store_dwordx4 v156, v[168:171], s[96:97] offset:64
	v_cvt_pk_bf16_f32 v164, v46, v47
	v_cvt_pk_bf16_f32 v165, v48, v49
	v_cvt_pk_bf16_f32 v166, v42, v43
	v_cvt_pk_bf16_f32 v167, v44, v45
	s_nop 1
	v_permlane16_swap_b32 v164, v166
	v_permlane16_swap_b32 v165, v167
	s_nop 1
	global_store_dwordx4 v157, v[164:167], s[96:97]
	v_cvt_pk_bf16_f32 v168, v38, v39
	v_cvt_pk_bf16_f32 v169, v40, v41
	v_cvt_pk_bf16_f32 v170, v34, v35
	v_cvt_pk_bf16_f32 v171, v36, v37
	s_nop 1
	v_permlane16_swap_b32 v168, v170
	v_permlane16_swap_b32 v169, v171
	s_nop 1
	global_store_dwordx4 v157, v[168:171], s[96:97] offset:64
	v_cvt_pk_bf16_f32 v164, v30, v31
	v_cvt_pk_bf16_f32 v165, v32, v33
	v_cvt_pk_bf16_f32 v166, v26, v27
	v_cvt_pk_bf16_f32 v167, v28, v29
	s_nop 1
	v_permlane16_swap_b32 v164, v166
	v_permlane16_swap_b32 v165, v167
	s_nop 1
	global_store_dwordx4 v158, v[164:167], s[96:97]
	v_cvt_pk_bf16_f32 v168, v22, v23
	v_cvt_pk_bf16_f32 v169, v24, v25
	v_cvt_pk_bf16_f32 v170, v18, v19
	v_cvt_pk_bf16_f32 v171, v20, v21
	s_nop 1
	v_permlane16_swap_b32 v168, v170
	v_permlane16_swap_b32 v169, v171
	s_nop 1
	global_store_dwordx4 v158, v[168:171], s[96:97] offset:64
	v_cvt_pk_bf16_f32 v164, v14, v15
	v_cvt_pk_bf16_f32 v165, v16, v17
	v_cvt_pk_bf16_f32 v166, v10, v11
	v_cvt_pk_bf16_f32 v167, v12, v13
	s_nop 1
	v_permlane16_swap_b32 v164, v166
	v_permlane16_swap_b32 v165, v167
	s_nop 1
	global_store_dwordx4 v159, v[164:167], s[96:97]
	v_cvt_pk_bf16_f32 v168, v6, v7
	v_cvt_pk_bf16_f32 v169, v8, v9
	v_cvt_pk_bf16_f32 v170, v2, v3
	v_cvt_pk_bf16_f32 v171, v4, v5
	s_nop 1
	v_permlane16_swap_b32 v168, v170
	v_permlane16_swap_b32 v169, v171
	s_nop 1
	global_store_dwordx4 v159, v[168:171], s[96:97] offset:64
	s_lshl_b32 s2, s49, 17
	s_lshl_b32 s38, s3, 8
	s_add_i32 s2, s2, s38
	s_add_u32 s96, s92, s2
	s_addc_u32 s97, s93, 0
	s_cmp_lt_u32 s49, 0x80
	s_cbranch_scc0 .Lg2_cs1
	s_lshl_b32 s2, s21, 25
	s_lshl_b32 s38, s49, 18
	s_add_i32 s2, s2, s38
	s_cmp_eq_u32 s20, 1
	s_mov_b32 s38, 0xa500000
	s_cmov_b32 s38, 0x6500000
	s_branch .Lg2_ct1
.Lg2_cs1:
	s_lshl_b32 s2, s21, 19
	s_sub_i32 s38, s49, 0x80
	s_lshl_b32 s38, s38, 18
	s_add_i32 s2, s2, s38
	s_cmp_eq_u32 s20, 1
	s_mov_b32 s38, 0xe690000
	s_cmov_b32 s38, 0xe590000
.Lg2_ct1:
	s_add_u32 s2, s2, s38
	s_lshl_b32 s38, s3, 9
	s_add_u32 s2, s2, s38
	s_add_u32 s88, s98, s2
	s_addc_u32 s89, s99, 0
	s_cmp_eq_u32 s20, 0
	s_cbranch_scc1 .Lg2_cb1
	global_store_dwordx4 v160, v[66:69], s[88:89] nt
	global_store_dwordx4 v160, v[70:73], s[88:89] offset:64 nt
	global_store_dwordx4 v160, v[82:85], s[88:89] offset:128 nt
	global_store_dwordx4 v160, v[88:91], s[88:89] offset:192 nt
	global_store_dwordx4 v161, v[92:95], s[88:89] nt
	global_store_dwordx4 v161, v[96:99], s[88:89] offset:64 nt
	global_store_dwordx4 v161, v[100:103], s[88:89] offset:128 nt
	global_store_dwordx4 v161, v[106:109], s[88:89] offset:192 nt
	global_store_dwordx4 v162, v[110:113], s[88:89] nt
	global_store_dwordx4 v162, v[114:117], s[88:89] offset:64 nt
	global_store_dwordx4 v162, v[118:121], s[88:89] offset:128 nt
	global_store_dwordx4 v162, v[122:125], s[88:89] offset:192 nt
	global_store_dwordx4 v163, v[126:129], s[88:89] nt
	global_store_dwordx4 v163, v[136:139], s[88:89] offset:64 nt
	global_store_dwordx4 v163, v[140:143], s[88:89] offset:128 nt
	global_store_dwordx4 v163, v[144:147], s[88:89] offset:192 nt
.Lg2_cb1:
	v_cvt_pk_bf16_f32 v164, v66, v67
	v_cvt_pk_bf16_f32 v165, v68, v69
	v_cvt_pk_bf16_f32 v166, v70, v71
	v_cvt_pk_bf16_f32 v167, v72, v73
	s_nop 1
	v_permlane16_swap_b32 v164, v166
	v_permlane16_swap_b32 v165, v167
	s_nop 1
	global_store_dwordx4 v156, v[164:167], s[96:97]
	v_cvt_pk_bf16_f32 v168, v82, v83
	v_cvt_pk_bf16_f32 v169, v84, v85
	v_cvt_pk_bf16_f32 v170, v88, v89
	v_cvt_pk_bf16_f32 v171, v90, v91
	s_nop 1
	v_permlane16_swap_b32 v168, v170
	v_permlane16_swap_b32 v169, v171
	s_nop 1
	global_store_dwordx4 v156, v[168:171], s[96:97] offset:64
	v_cvt_pk_bf16_f32 v164, v92, v93
	v_cvt_pk_bf16_f32 v165, v94, v95
	v_cvt_pk_bf16_f32 v166, v96, v97
	v_cvt_pk_bf16_f32 v167, v98, v99
	s_nop 1
	v_permlane16_swap_b32 v164, v166
	v_permlane16_swap_b32 v165, v167
	s_nop 1
	global_store_dwordx4 v157, v[164:167], s[96:97]
	v_cvt_pk_bf16_f32 v168, v100, v101
	v_cvt_pk_bf16_f32 v169, v102, v103
	v_cvt_pk_bf16_f32 v170, v106, v107
	v_cvt_pk_bf16_f32 v171, v108, v109
	s_nop 1
	v_permlane16_swap_b32 v168, v170
	v_permlane16_swap_b32 v169, v171
	s_nop 1
	global_store_dwordx4 v157, v[168:171], s[96:97] offset:64
	v_cvt_pk_bf16_f32 v164, v110, v111
	v_cvt_pk_bf16_f32 v165, v112, v113
	v_cvt_pk_bf16_f32 v166, v114, v115
	v_cvt_pk_bf16_f32 v167, v116, v117
	s_nop 1
	v_permlane16_swap_b32 v164, v166
	v_permlane16_swap_b32 v165, v167
	s_nop 1
	global_store_dwordx4 v158, v[164:167], s[96:97]
	v_cvt_pk_bf16_f32 v168, v118, v119
	v_cvt_pk_bf16_f32 v169, v120, v121
	v_cvt_pk_bf16_f32 v170, v122, v123
	v_cvt_pk_bf16_f32 v171, v124, v125
	s_nop 1
	v_permlane16_swap_b32 v168, v170
	v_permlane16_swap_b32 v169, v171
	s_nop 1
	global_store_dwordx4 v158, v[168:171], s[96:97] offset:64
	v_cvt_pk_bf16_f32 v164, v126, v127
	v_cvt_pk_bf16_f32 v165, v128, v129
	v_cvt_pk_bf16_f32 v166, v136, v137
	v_cvt_pk_bf16_f32 v167, v138, v139
	s_nop 1
	v_permlane16_swap_b32 v164, v166
	v_permlane16_swap_b32 v165, v167
	s_nop 1
	global_store_dwordx4 v159, v[164:167], s[96:97]
	v_cvt_pk_bf16_f32 v168, v140, v141
	v_cvt_pk_bf16_f32 v169, v142, v143
	v_cvt_pk_bf16_f32 v170, v144, v145
	v_cvt_pk_bf16_f32 v171, v146, v147
	s_nop 1
	v_permlane16_swap_b32 v168, v170
	v_permlane16_swap_b32 v169, v171
	s_nop 1
	global_store_dwordx4 v159, v[168:171], s[96:97] offset:64
	s_branch .Lg2_next
